# C2b (NSA attention) unit->block remap: co-resident blocks b/b+256 get complementary query blocks (kq, 31-kq) to balance per-SIMD work
# baseline (speedup 1.0000x reference)
; DI void phaseC2b(const Params& p, const float* lut, bool dry) {
;     ...
;   for (int u = blockIdx.x * 4 + wid; u < 4096; u += gridDim.x * 4) {
;     const int itp = (u >> 11) & 1, kq = (u >> 6) & 31;
;     const int qb = itp ? kq : 63 - kq, b = (u >> 2) & 15, hd = u & 3;
;     const int t = qb * 32 + r;
;     const size_t tok = (size_t)b * SEQ + t;
.LBB0_29:
	v_bfe_i32 v0, v133, 10, 1
	v_and_b32_e32 v3, 0x800, v133
	v_bfe_u32 v2, v133, 2, 5
	v_and_b32_e32 v0, 31, v0
	v_xor_b32_e32 v2, v2, v0
	v_xor_b32_e32 v0, 63, v2
	v_cmp_eq_u32_e32 vcc, 0, v3
	v_bfe_u32 v4, v133, 7, 4
	v_readlane_b32 s52, v253, 11
	v_cndmask_b32_e32 v196, v2, v0, vcc
	v_lshlrev_b32_e32 v5, 5, v196
	v_or_b32_e32 v197, v5, v194
	v_lshl_or_b32 v164, v4, 11, v197
	v_mad_u64_u32 v[2:3], s[0:1], v164, s50, v[134:135]
	v_lshlrev_b32_e32 v0, 2, v164
	v_readlane_b32 s58, v253, 17
	v_readlane_b32 s59, v253, 18
	global_load_dwordx4 v[66:69], v[2:3], off offset:512
	global_load_dwordx4 v[70:73], v[2:3], off offset:544
	global_load_dwordx4 v[74:77], v[2:3], off offset:576
	global_load_dwordx4 v[78:81], v[2:3], off offset:608
	v_readlane_b32 s16, v250, 34
	global_load_dword v198, v0, s[58:59]
	v_lshlrev_b32_e32 v0, 7, v164
	v_lshl_add_u64 v[2:3], v[136:137], 0, v[0:1]
	global_load_dwordx3 v[130:132], v[2:3], off offset:64
	v_readlane_b32 s53, v253, 12
	v_lshlrev_b32_e32 v0, 18, v4
	v_readlane_b32 s20, v250, 38
	v_readlane_b32 s21, v250, 39
	v_readlane_b32 s22, v250, 40
	v_readlane_b32 s23, v250, 41
	v_readlane_b32 s30, v250, 48
	v_readlane_b32 s31, v250, 49
	v_readlane_b32 s26, v250, 44
	v_readlane_b32 s27, v250, 45
	v_readlane_b32 s28, v250, 46
	v_readlane_b32 s29, v250, 47
	v_lshl_add_u64 v[170:171], s[22:23], 0, v[0:1]
	v_lshl_add_u64 v[172:173], s[52:53], 0, v[0:1]
	v_lshl_add_u64 v[174:175], s[30:31], 0, v[0:1]
	v_lshl_add_u64 v[176:177], s[20:21], 0, v[0:1]
	v_lshlrev_b32_e32 v0, 14, v4
	v_lshl_add_u64 v[178:179], s[26:27], 0, v[0:1]
	v_lshl_add_u64 v[182:183], s[28:29], 0, v[0:1]
	v_min_u32_e32 v0, 16, v196
	v_sub_u32_e64 v199, v196, 16 clamp
	v_add_u32_e32 v200, 1, v196
	v_lshlrev_b32_e32 v0, 5, v0
	v_lshlrev_b32_e32 v2, 11, v199
	v_and_b32_e32 v201, 0x78, v200
	v_or_b32_e32 v202, v194, v0
	v_sub_u32_e32 v0, v0, v5
	v_mov_b32_e32 v156, 0
	s_mov_b32 s10, 0
	v_mov_b32_e32 v165, v1
	v_cmp_lt_u32_e64 s[0:1], 14, v196
	v_cmp_ne_u32_e64 s[4:5], v200, v201
	v_subrev_u32_e32 v203, 31, v0
	v_lshlrev_b32_e32 v186, 1, v2
	v_mov_b32_e32 v157, v156
	v_mov_b32_e32 v184, v156
	v_mov_b32_e32 v185, v156
	v_mov_b32_e32 v180, v156
	v_mov_b32_e32 v181, v156
	v_mov_b32_e32 v168, v156
	v_mov_b32_e32 v169, v156
	v_mov_b32_e32 v166, v156
	v_mov_b32_e32 v167, v156
	v_mov_b32_e32 v162, v156
	v_mov_b32_e32 v163, v156
	v_mov_b32_e32 v160, v156
	v_mov_b32_e32 v161, v156
	v_mov_b32_e32 v158, v156
	v_mov_b32_e32 v159, v156
	v_mov_b32_e32 v140, v156
	v_mov_b32_e32 v141, v156
	v_mov_b32_e32 v154, v156
	v_mov_b32_e32 v155, v156
	v_mov_b32_e32 v152, v156
	v_mov_b32_e32 v153, v156
	v_mov_b32_e32 v150, v156
	v_mov_b32_e32 v151, v156
	v_mov_b32_e32 v148, v156
	v_mov_b32_e32 v149, v156
	v_mov_b32_e32 v146, v156
	v_mov_b32_e32 v147, v156
	v_mov_b32_e32 v144, v156
	v_mov_b32_e32 v145, v156
	v_mov_b32_e32 v142, v156
	v_mov_b32_e32 v143, v156
	v_readlane_b32 s54, v253, 13
	v_readlane_b32 s55, v253, 14
	v_readlane_b32 s56, v253, 15
	v_readlane_b32 s57, v253, 16
	v_readlane_b32 s60, v253, 19
	v_readlane_b32 s61, v253, 20
	v_readlane_b32 s62, v253, 21
	v_readlane_b32 s63, v253, 22
	v_readlane_b32 s64, v253, 23
	v_readlane_b32 s65, v253, 24
	v_readlane_b32 s66, v253, 25
	v_readlane_b32 s67, v253, 26
	v_readlane_b32 s17, v250, 35
	v_readlane_b32 s18, v250, 36
	v_readlane_b32 s19, v250, 37
	v_readlane_b32 s24, v250, 42
	v_readlane_b32 s25, v250, 43
	s_branch .LBB0_31
